# MoBA block means (phase C): 16-byte loads, 16 in flight, lane butterfly instead of 256 dependent 2-byte loads in batches of 8
# speedup vs baseline: 1.0064x; 1.0047x over previous
; __device__ __forceinline__ float bf2f(unsigned v16) { return __uint_as_float(v16 << 16); }
; __global__ void __launch_bounds__(512, 2) hybrid_fwd(Params P) {
;     ...
;                 const bf16_t* mbk = (const bf16_t*)(ws + WS_B + HB_MBK * MiB); float* KMEAN = (float*)(ws + WS_SMALL + 4096);
;                 for (int item = (bx - 128) * 8 + wave; item < 512; item += (G - 128) * 8) { const int bh = item >> 5, n = item & 31;
;                     const bf16_t* kp = mbk + ((size_t)bh * SEQ + 256 * n) * 64 + lane; float a = 0.f;
; #pragma unroll 8
;                     for (int j = 0; j < 256; ++j) a += bf2f(kp[(size_t)j * 64]);
;                     KMEAN[(size_t)item * 64 + lane] = a * (1.0f / 256.0f); }
.LBB0_740:
	s_nop 0
	s_nop 0
	s_nop 0
	s_nop 0
	s_nop 0
	s_nop 0
	s_nop 0
	s_nop 0
	s_nop 0
	s_nop 0
	s_or_b64 exec, exec, s[4:5]
	v_readlane_b32 s4, v255, 17
	s_barrier
	s_mov_b64 s[6:7], s[58:59]
	s_mov_b32 s28, s69
	s_mov_b32 s10, s2
	v_mov_b32_e32 v8, v146
	s_cmpk_gt_i32 s10, 0x7f
	v_readfirstlane_b32 s8, v8
	s_mov_b64 s[4:5], -1
	s_cbranch_scc0 .LBB0_747
	s_ashr_i32 s4, s8, 6
	s_lshl_b32 s5, s10, 3
	s_add_i32 s4, s5, s4
	s_addk_i32 s4, 0xfc00
	s_cmpk_gt_i32 s4, 0x1ff
	s_cbranch_scc1 .LBB0_746
	v_and_b32_e32 v2, 63, v8
	v_lshlrev_b32_e32 v80, 2, v2
	v_lshl_add_u64 v[0:1], s[6:7], 0, v[80:81]
	s_mov_b64 s[8:9], 0x2401000
	v_lshlrev_b32_e32 v80, 1, v2
	v_lshl_add_u64 v[0:1], v[0:1], 0, s[8:9]
	s_lshl_b32 s11, s28, 3
	v_lshl_add_u64 v[2:3], s[6:7], 0, v[80:81]
	s_mov_b64 s[8:9], 0x17100200
	s_lshl_b32 s13, s28, 17
	s_addk_i32 s11, 0xfc00
	v_lshl_add_u64 v[2:3], v[2:3], 0, s[8:9]
	s_lshl_b32 s12, s4, 14
	s_add_i32 s13, s13, 0xff000000
.LBB0_743:
	s_ashr_i32 s8, s4, 5
	s_lshl_b32 s5, s12, 1
	s_ashr_i32 s9, s8, 31
	s_and_b32 s5, s5, 0xf8000
	s_lshl_b64 s[8:9], s[8:9], 20
	s_or_b32 s8, s8, s5
	v_lshl_add_u64 v[4:5], v[2:3], 0, s[8:9]
	v_mov_b32_e32 v6, 0
	s_mov_b64 s[8:9], 0
	v_and_b32_e32 v17, 63, v146
	v_mul_u32_u24_e32 v18, 14, v17
	v_mov_b32_e32 v19, 0
	v_lshl_add_u64 v[20:21], v[18:19], 0, v[4:5]
	s_mov_b64 s[8:9], 0xe00
	v_lshl_add_u64 v[20:21], v[20:21], 0, s[8:9]
	s_mov_b64 s[8:9], 0x2000
	v_lshl_add_u64 v[22:23], v[20:21], 0, s[8:9]
	v_mov_b32_e32 v24, 0
	v_mov_b32_e32 v25, 0
	v_mov_b32_e32 v26, 0
	v_mov_b32_e32 v27, 0
	v_mov_b32_e32 v28, 0
	v_mov_b32_e32 v29, 0
	v_mov_b32_e32 v30, 0
	v_mov_b32_e32 v31, 0
	s_mov_b32 s5, 0
.Lkm_round:
	global_load_dwordx4 v[82:85], v[20:21], off offset:-4096
	global_load_dwordx4 v[86:89], v[20:21], off offset:-3072
	global_load_dwordx4 v[90:93], v[20:21], off offset:-2048
	global_load_dwordx4 v[94:97], v[20:21], off offset:-1024
	global_load_dwordx4 v[98:101], v[20:21], off offset:0
	global_load_dwordx4 v[102:105], v[20:21], off offset:1024
	global_load_dwordx4 v[106:109], v[20:21], off offset:2048
	global_load_dwordx4 v[110:113], v[20:21], off offset:3072
	global_load_dwordx4 v[114:117], v[22:23], off offset:-4096
	global_load_dwordx4 v[118:121], v[22:23], off offset:-3072
	global_load_dwordx4 v[122:125], v[22:23], off offset:-2048
	global_load_dwordx4 v[126:129], v[22:23], off offset:-1024
	global_load_dwordx4 v[130:133], v[22:23], off offset:0
	global_load_dwordx4 v[134:137], v[22:23], off offset:1024
	global_load_dwordx4 v[138:141], v[22:23], off offset:2048
	global_load_dwordx4 v[142:145], v[22:23], off offset:3072
	s_mov_b64 s[8:9], 0x4000
	v_lshl_add_u64 v[20:21], v[20:21], 0, s[8:9]
	v_lshl_add_u64 v[22:23], v[22:23], 0, s[8:9]
	s_waitcnt vmcnt(15)
	v_lshlrev_b32_e32 v16, 16, v82
	v_and_b32_e32 v32, 0xffff0000, v82
	v_add_f32_e32 v24, v24, v16
	v_add_f32_e32 v25, v25, v32
	v_lshlrev_b32_e32 v16, 16, v83
	v_and_b32_e32 v32, 0xffff0000, v83
	v_add_f32_e32 v26, v26, v16
	v_add_f32_e32 v27, v27, v32
	v_lshlrev_b32_e32 v16, 16, v84
	v_and_b32_e32 v32, 0xffff0000, v84
	v_add_f32_e32 v28, v28, v16
	v_add_f32_e32 v29, v29, v32
	v_lshlrev_b32_e32 v16, 16, v85
	v_and_b32_e32 v32, 0xffff0000, v85
	v_add_f32_e32 v30, v30, v16
	v_add_f32_e32 v31, v31, v32
	s_waitcnt vmcnt(14)
	v_lshlrev_b32_e32 v16, 16, v86
	v_and_b32_e32 v32, 0xffff0000, v86
	v_add_f32_e32 v24, v24, v16
	v_add_f32_e32 v25, v25, v32
	v_lshlrev_b32_e32 v16, 16, v87
	v_and_b32_e32 v32, 0xffff0000, v87
	v_add_f32_e32 v26, v26, v16
	v_add_f32_e32 v27, v27, v32
	v_lshlrev_b32_e32 v16, 16, v88
	v_and_b32_e32 v32, 0xffff0000, v88
	v_add_f32_e32 v28, v28, v16
	v_add_f32_e32 v29, v29, v32
	v_lshlrev_b32_e32 v16, 16, v89
	v_and_b32_e32 v32, 0xffff0000, v89
	v_add_f32_e32 v30, v30, v16
	v_add_f32_e32 v31, v31, v32
	s_waitcnt vmcnt(13)
	v_lshlrev_b32_e32 v16, 16, v90
	v_and_b32_e32 v32, 0xffff0000, v90
	v_add_f32_e32 v24, v24, v16
	v_add_f32_e32 v25, v25, v32
	v_lshlrev_b32_e32 v16, 16, v91
	v_and_b32_e32 v32, 0xffff0000, v91
	v_add_f32_e32 v26, v26, v16
	v_add_f32_e32 v27, v27, v32
	v_lshlrev_b32_e32 v16, 16, v92
	v_and_b32_e32 v32, 0xffff0000, v92
	v_add_f32_e32 v28, v28, v16
	v_add_f32_e32 v29, v29, v32
	v_lshlrev_b32_e32 v16, 16, v93
	v_and_b32_e32 v32, 0xffff0000, v93
	v_add_f32_e32 v30, v30, v16
	v_add_f32_e32 v31, v31, v32
	s_waitcnt vmcnt(12)
	v_lshlrev_b32_e32 v16, 16, v94
	v_and_b32_e32 v32, 0xffff0000, v94
	v_add_f32_e32 v24, v24, v16
	v_add_f32_e32 v25, v25, v32
	v_lshlrev_b32_e32 v16, 16, v95
	v_and_b32_e32 v32, 0xffff0000, v95
	v_add_f32_e32 v26, v26, v16
	v_add_f32_e32 v27, v27, v32
	v_lshlrev_b32_e32 v16, 16, v96
	v_and_b32_e32 v32, 0xffff0000, v96
	v_add_f32_e32 v28, v28, v16
	v_add_f32_e32 v29, v29, v32
	v_lshlrev_b32_e32 v16, 16, v97
	v_and_b32_e32 v32, 0xffff0000, v97
	v_add_f32_e32 v30, v30, v16
	v_add_f32_e32 v31, v31, v32
	s_waitcnt vmcnt(11)
	v_lshlrev_b32_e32 v16, 16, v98
	v_and_b32_e32 v32, 0xffff0000, v98
	v_add_f32_e32 v24, v24, v16
	v_add_f32_e32 v25, v25, v32
	v_lshlrev_b32_e32 v16, 16, v99
	v_and_b32_e32 v32, 0xffff0000, v99
	v_add_f32_e32 v26, v26, v16
	v_add_f32_e32 v27, v27, v32
	v_lshlrev_b32_e32 v16, 16, v100
	v_and_b32_e32 v32, 0xffff0000, v100
	v_add_f32_e32 v28, v28, v16
	v_add_f32_e32 v29, v29, v32
	v_lshlrev_b32_e32 v16, 16, v101
	v_and_b32_e32 v32, 0xffff0000, v101
	v_add_f32_e32 v30, v30, v16
	v_add_f32_e32 v31, v31, v32
	s_waitcnt vmcnt(10)
	v_lshlrev_b32_e32 v16, 16, v102
	v_and_b32_e32 v32, 0xffff0000, v102
	v_add_f32_e32 v24, v24, v16
	v_add_f32_e32 v25, v25, v32
	v_lshlrev_b32_e32 v16, 16, v103
	v_and_b32_e32 v32, 0xffff0000, v103
	v_add_f32_e32 v26, v26, v16
	v_add_f32_e32 v27, v27, v32
	v_lshlrev_b32_e32 v16, 16, v104
	v_and_b32_e32 v32, 0xffff0000, v104
	v_add_f32_e32 v28, v28, v16
	v_add_f32_e32 v29, v29, v32
	v_lshlrev_b32_e32 v16, 16, v105
	v_and_b32_e32 v32, 0xffff0000, v105
	v_add_f32_e32 v30, v30, v16
	v_add_f32_e32 v31, v31, v32
	s_waitcnt vmcnt(9)
; __device__ __forceinline__ float bf2f(unsigned v16) { return __uint_as_float(v16 << 16); }
; __global__ void __launch_bounds__(512, 2) hybrid_fwd(Params P) {
;     ...
;                     const bf16_t* kp = mbk + ((size_t)bh * SEQ + 256 * n) * 64 + lane; float a = 0.f;
; #pragma unroll 8
;                     for (int j = 0; j < 256; ++j) a += bf2f(kp[(size_t)j * 64]);
	v_lshlrev_b32_e32 v16, 16, v106
	v_and_b32_e32 v32, 0xffff0000, v106
	v_add_f32_e32 v24, v24, v16
	v_add_f32_e32 v25, v25, v32
	v_lshlrev_b32_e32 v16, 16, v107
	v_and_b32_e32 v32, 0xffff0000, v107
	v_add_f32_e32 v26, v26, v16
	v_add_f32_e32 v27, v27, v32
	v_lshlrev_b32_e32 v16, 16, v108
	v_and_b32_e32 v32, 0xffff0000, v108
	v_add_f32_e32 v28, v28, v16
	v_add_f32_e32 v29, v29, v32
	v_lshlrev_b32_e32 v16, 16, v109
	v_and_b32_e32 v32, 0xffff0000, v109
	v_add_f32_e32 v30, v30, v16
	v_add_f32_e32 v31, v31, v32
	s_waitcnt vmcnt(8)
	v_lshlrev_b32_e32 v16, 16, v110
	v_and_b32_e32 v32, 0xffff0000, v110
	v_add_f32_e32 v24, v24, v16
	v_add_f32_e32 v25, v25, v32
	v_lshlrev_b32_e32 v16, 16, v111
	v_and_b32_e32 v32, 0xffff0000, v111
	v_add_f32_e32 v26, v26, v16
	v_add_f32_e32 v27, v27, v32
	v_lshlrev_b32_e32 v16, 16, v112
	v_and_b32_e32 v32, 0xffff0000, v112
	v_add_f32_e32 v28, v28, v16
	v_add_f32_e32 v29, v29, v32
	v_lshlrev_b32_e32 v16, 16, v113
	v_and_b32_e32 v32, 0xffff0000, v113
	v_add_f32_e32 v30, v30, v16
	v_add_f32_e32 v31, v31, v32
	s_waitcnt vmcnt(7)
	v_lshlrev_b32_e32 v16, 16, v114
	v_and_b32_e32 v32, 0xffff0000, v114
	v_add_f32_e32 v24, v24, v16
	v_add_f32_e32 v25, v25, v32
	v_lshlrev_b32_e32 v16, 16, v115
	v_and_b32_e32 v32, 0xffff0000, v115
	v_add_f32_e32 v26, v26, v16
	v_add_f32_e32 v27, v27, v32
	v_lshlrev_b32_e32 v16, 16, v116
	v_and_b32_e32 v32, 0xffff0000, v116
	v_add_f32_e32 v28, v28, v16
	v_add_f32_e32 v29, v29, v32
	v_lshlrev_b32_e32 v16, 16, v117
	v_and_b32_e32 v32, 0xffff0000, v117
	v_add_f32_e32 v30, v30, v16
	v_add_f32_e32 v31, v31, v32
	s_waitcnt vmcnt(6)
	v_lshlrev_b32_e32 v16, 16, v118
	v_and_b32_e32 v32, 0xffff0000, v118
	v_add_f32_e32 v24, v24, v16
	v_add_f32_e32 v25, v25, v32
	v_lshlrev_b32_e32 v16, 16, v119
	v_and_b32_e32 v32, 0xffff0000, v119
	v_add_f32_e32 v26, v26, v16
	v_add_f32_e32 v27, v27, v32
	v_lshlrev_b32_e32 v16, 16, v120
	v_and_b32_e32 v32, 0xffff0000, v120
	v_add_f32_e32 v28, v28, v16
	v_add_f32_e32 v29, v29, v32
	v_lshlrev_b32_e32 v16, 16, v121
	v_and_b32_e32 v32, 0xffff0000, v121
	v_add_f32_e32 v30, v30, v16
	v_add_f32_e32 v31, v31, v32
	s_waitcnt vmcnt(5)
	v_lshlrev_b32_e32 v16, 16, v122
	v_and_b32_e32 v32, 0xffff0000, v122
	v_add_f32_e32 v24, v24, v16
	v_add_f32_e32 v25, v25, v32
	v_lshlrev_b32_e32 v16, 16, v123
	v_and_b32_e32 v32, 0xffff0000, v123
	v_add_f32_e32 v26, v26, v16
	v_add_f32_e32 v27, v27, v32
	v_lshlrev_b32_e32 v16, 16, v124
	v_and_b32_e32 v32, 0xffff0000, v124
	v_add_f32_e32 v28, v28, v16
	v_add_f32_e32 v29, v29, v32
	v_lshlrev_b32_e32 v16, 16, v125
	v_and_b32_e32 v32, 0xffff0000, v125
	v_add_f32_e32 v30, v30, v16
	v_add_f32_e32 v31, v31, v32
	s_waitcnt vmcnt(4)
	v_lshlrev_b32_e32 v16, 16, v126
	v_and_b32_e32 v32, 0xffff0000, v126
	v_add_f32_e32 v24, v24, v16
	v_add_f32_e32 v25, v25, v32
	v_lshlrev_b32_e32 v16, 16, v127
	v_and_b32_e32 v32, 0xffff0000, v127
	v_add_f32_e32 v26, v26, v16
	v_add_f32_e32 v27, v27, v32
	v_lshlrev_b32_e32 v16, 16, v128
	v_and_b32_e32 v32, 0xffff0000, v128
	v_add_f32_e32 v28, v28, v16
	v_add_f32_e32 v29, v29, v32
	v_lshlrev_b32_e32 v16, 16, v129
	v_and_b32_e32 v32, 0xffff0000, v129
	v_add_f32_e32 v30, v30, v16
	v_add_f32_e32 v31, v31, v32
	s_waitcnt vmcnt(3)
	v_lshlrev_b32_e32 v16, 16, v130
	v_and_b32_e32 v32, 0xffff0000, v130
	v_add_f32_e32 v24, v24, v16
	v_add_f32_e32 v25, v25, v32
	v_lshlrev_b32_e32 v16, 16, v131
	v_and_b32_e32 v32, 0xffff0000, v131
	v_add_f32_e32 v26, v26, v16
	v_add_f32_e32 v27, v27, v32
	v_lshlrev_b32_e32 v16, 16, v132
	v_and_b32_e32 v32, 0xffff0000, v132
	v_add_f32_e32 v28, v28, v16
	v_add_f32_e32 v29, v29, v32
	v_lshlrev_b32_e32 v16, 16, v133
	v_and_b32_e32 v32, 0xffff0000, v133
	v_add_f32_e32 v30, v30, v16
	v_add_f32_e32 v31, v31, v32
	s_waitcnt vmcnt(2)
	v_lshlrev_b32_e32 v16, 16, v134
	v_and_b32_e32 v32, 0xffff0000, v134
	v_add_f32_e32 v24, v24, v16
	v_add_f32_e32 v25, v25, v32
	v_lshlrev_b32_e32 v16, 16, v135
	v_and_b32_e32 v32, 0xffff0000, v135
	v_add_f32_e32 v26, v26, v16
	v_add_f32_e32 v27, v27, v32
	v_lshlrev_b32_e32 v16, 16, v136
	v_and_b32_e32 v32, 0xffff0000, v136
	v_add_f32_e32 v28, v28, v16
	v_add_f32_e32 v29, v29, v32
	v_lshlrev_b32_e32 v16, 16, v137
	v_and_b32_e32 v32, 0xffff0000, v137
	v_add_f32_e32 v30, v30, v16
	v_add_f32_e32 v31, v31, v32
	s_waitcnt vmcnt(1)
	v_lshlrev_b32_e32 v16, 16, v138
	v_and_b32_e32 v32, 0xffff0000, v138
	v_add_f32_e32 v24, v24, v16
	v_add_f32_e32 v25, v25, v32
	v_lshlrev_b32_e32 v16, 16, v139
	v_and_b32_e32 v32, 0xffff0000, v139
	v_add_f32_e32 v26, v26, v16
	v_add_f32_e32 v27, v27, v32
	v_lshlrev_b32_e32 v16, 16, v140
	v_and_b32_e32 v32, 0xffff0000, v140
	v_add_f32_e32 v28, v28, v16
	v_add_f32_e32 v29, v29, v32
	v_lshlrev_b32_e32 v16, 16, v141
	v_and_b32_e32 v32, 0xffff0000, v141
	v_add_f32_e32 v30, v30, v16
	v_add_f32_e32 v31, v31, v32
	s_waitcnt vmcnt(0)
	v_lshlrev_b32_e32 v16, 16, v142
	v_and_b32_e32 v32, 0xffff0000, v142
	v_add_f32_e32 v24, v24, v16
	v_add_f32_e32 v25, v25, v32
	v_lshlrev_b32_e32 v16, 16, v143
	v_and_b32_e32 v32, 0xffff0000, v143
	v_add_f32_e32 v26, v26, v16
	v_add_f32_e32 v27, v27, v32
	v_lshlrev_b32_e32 v16, 16, v144
	v_and_b32_e32 v32, 0xffff0000, v144
	v_add_f32_e32 v28, v28, v16
	v_add_f32_e32 v29, v29, v32
	v_lshlrev_b32_e32 v16, 16, v145
	v_and_b32_e32 v32, 0xffff0000, v145
	v_add_f32_e32 v30, v30, v16
	v_add_f32_e32 v31, v31, v32
	s_add_u32 s5, s5, 1
	s_cmp_lt_u32 s5, 2
	s_cbranch_scc1 .Lkm_round
; __device__ __forceinline__ float bf2f(unsigned v16) { return __uint_as_float(v16 << 16); }
; __global__ void __launch_bounds__(512, 2) hybrid_fwd(Params P) {
;     ...
;                     for (int j = 0; j < 256; ++j) a += bf2f(kp[(size_t)j * 64]);
;                     KMEAN[(size_t)item * 64 + lane] = a * (1.0f / 256.0f); }
	v_xor_b32_e32 v18, 8, v17
	v_lshlrev_b32_e32 v18, 2, v18
	ds_bpermute_b32 v33, v18, v24
	ds_bpermute_b32 v34, v18, v25
	ds_bpermute_b32 v35, v18, v26
	ds_bpermute_b32 v36, v18, v27
	ds_bpermute_b32 v37, v18, v28
	ds_bpermute_b32 v38, v18, v29
	ds_bpermute_b32 v39, v18, v30
	ds_bpermute_b32 v40, v18, v31
	s_waitcnt lgkmcnt(7)
	v_add_f32_e32 v24, v24, v33
	s_waitcnt lgkmcnt(6)
	v_add_f32_e32 v25, v25, v34
	s_waitcnt lgkmcnt(5)
	v_add_f32_e32 v26, v26, v35
	s_waitcnt lgkmcnt(4)
	v_add_f32_e32 v27, v27, v36
	s_waitcnt lgkmcnt(3)
	v_add_f32_e32 v28, v28, v37
	s_waitcnt lgkmcnt(2)
	v_add_f32_e32 v29, v29, v38
	s_waitcnt lgkmcnt(1)
	v_add_f32_e32 v30, v30, v39
	s_waitcnt lgkmcnt(0)
	v_add_f32_e32 v31, v31, v40
	v_xor_b32_e32 v18, 16, v17
	v_lshlrev_b32_e32 v18, 2, v18
	ds_bpermute_b32 v33, v18, v24
	ds_bpermute_b32 v34, v18, v25
	ds_bpermute_b32 v35, v18, v26
	ds_bpermute_b32 v36, v18, v27
	ds_bpermute_b32 v37, v18, v28
	ds_bpermute_b32 v38, v18, v29
	ds_bpermute_b32 v39, v18, v30
	ds_bpermute_b32 v40, v18, v31
	s_waitcnt lgkmcnt(7)
	v_add_f32_e32 v24, v24, v33
	s_waitcnt lgkmcnt(6)
	v_add_f32_e32 v25, v25, v34
	s_waitcnt lgkmcnt(5)
	v_add_f32_e32 v26, v26, v35
	s_waitcnt lgkmcnt(4)
	v_add_f32_e32 v27, v27, v36
	s_waitcnt lgkmcnt(3)
	v_add_f32_e32 v28, v28, v37
	s_waitcnt lgkmcnt(2)
	v_add_f32_e32 v29, v29, v38
	s_waitcnt lgkmcnt(1)
	v_add_f32_e32 v30, v30, v39
	s_waitcnt lgkmcnt(0)
	v_add_f32_e32 v31, v31, v40
	v_xor_b32_e32 v18, 32, v17
	v_lshlrev_b32_e32 v18, 2, v18
	ds_bpermute_b32 v33, v18, v24
	ds_bpermute_b32 v34, v18, v25
	ds_bpermute_b32 v35, v18, v26
	ds_bpermute_b32 v36, v18, v27
	ds_bpermute_b32 v37, v18, v28
	ds_bpermute_b32 v38, v18, v29
	ds_bpermute_b32 v39, v18, v30
	ds_bpermute_b32 v40, v18, v31
	s_waitcnt lgkmcnt(7)
	v_add_f32_e32 v24, v24, v33
	s_waitcnt lgkmcnt(6)
	v_add_f32_e32 v25, v25, v34
	s_waitcnt lgkmcnt(5)
	v_add_f32_e32 v26, v26, v35
	s_waitcnt lgkmcnt(4)
	v_add_f32_e32 v27, v27, v36
	s_waitcnt lgkmcnt(3)
	v_add_f32_e32 v28, v28, v37
	s_waitcnt lgkmcnt(2)
	v_add_f32_e32 v29, v29, v38
	s_waitcnt lgkmcnt(1)
	v_add_f32_e32 v30, v30, v39
	s_waitcnt lgkmcnt(0)
	v_add_f32_e32 v31, v31, v40
	v_mul_f32_e32 v24, 0x3b800000, v24
	v_mul_f32_e32 v25, 0x3b800000, v25
	v_mul_f32_e32 v26, 0x3b800000, v26
	v_mul_f32_e32 v27, 0x3b800000, v27
	v_mul_f32_e32 v28, 0x3b800000, v28
	v_mul_f32_e32 v29, 0x3b800000, v29
	v_mul_f32_e32 v30, 0x3b800000, v30
	v_mul_f32_e32 v31, 0x3b800000, v31
	s_ashr_i32 s5, s4, 31
	s_lshl_b64 s[8:9], s[4:5], 8
	v_mul_u32_u24_e32 v18, 28, v17
	v_lshl_add_u64 v[4:5], v[0:1], 0, s[8:9]
	v_lshl_add_u64 v[4:5], v[18:19], 0, v[4:5]
	s_mov_b64 exec, 0xff
	global_store_dwordx4 v[4:5], v[24:27], off
	global_store_dwordx4 v[4:5], v[28:31], off offset:16
	s_mov_b64 exec, -1
	s_add_i32 s4, s11, s4
	s_add_i32 s12, s12, s13
	s_cmpk_gt_i32 s4, 0x1ff
	s_cbranch_scc0 .LBB0_743
